# gdn_scan: stager waves touch chunk n+2's source lines (4-byte loads into unused registers) after issuing chunk n+1's LDS-DMA, landing wait vmcnt(11)
# baseline (speedup 1.0000x reference)
.LBB0_545:
	s_cmp_eq_u32 s87, 63
	s_cbranch_scc1 .Lscan_touch_skip
	s_add_i32 s99, s87, 2
	s_min_u32 s99, s99, 63
	s_mov_b32 s101, 0
	v_readlane_b32 s98, v255, 35
	s_nop 0
	s_lshl_b32 s100, s99, s98
	s_nop 0
	v_lshl_add_u64 v[18:19], v[94:95], 0, s[100:101]
	global_load_dword v180, v[18:19], off
	v_readlane_b32 s98, v255, 39
	s_nop 0
	s_lshl_b32 s100, s99, s98
	s_nop 0
	v_lshl_add_u64 v[18:19], v[96:97], 0, s[100:101]
	global_load_dword v181, v[18:19], off
	v_readlane_b32 s98, v255, 43
	s_nop 0
	s_lshl_b32 s100, s99, s98
	s_nop 0
	v_lshl_add_u64 v[18:19], v[98:99], 0, s[100:101]
	global_load_dword v182, v[18:19], off
	v_readlane_b32 s98, v255, 47
	s_nop 0
	s_lshl_b32 s100, s99, s98
	s_nop 0
	v_lshl_add_u64 v[18:19], v[100:101], 0, s[100:101]
	global_load_dword v183, v[18:19], off
	s_lshl_b32 s100, s99, s89
	s_nop 0
	v_lshl_add_u64 v[18:19], v[102:103], 0, s[100:101]
	global_load_dword v184, v[18:19], off
	s_lshl_b32 s100, s99, s34
	s_nop 0
	v_lshl_add_u64 v[18:19], v[104:105], 0, s[100:101]
	global_load_dword v185, v[18:19], off
	s_lshl_b32 s100, s99, s2
	s_nop 0
	v_lshl_add_u64 v[18:19], v[106:107], 0, s[100:101]
	global_load_dword v186, v[18:19], off
	s_lshl_b32 s100, s99, s82
	s_nop 0
	v_lshl_add_u64 v[18:19], v[108:109], 0, s[100:101]
	global_load_dword v187, v[18:19], off
	s_lshl_b32 s100, s99, s84
	s_nop 0
	v_lshl_add_u64 v[18:19], v[110:111], 0, s[100:101]
	global_load_dword v188, v[18:19], off
	s_lshl_b32 s100, s99, s5
	s_nop 0
	v_lshl_add_u64 v[18:19], v[112:113], 0, s[100:101]
	global_load_dword v189, v[18:19], off
	s_lshl_b32 s100, s99, s13
	s_nop 0
	v_lshl_add_u64 v[18:19], v[114:115], 0, s[100:101]
	global_load_dword v190, v[18:19], off

.LBB0_546:
	s_waitcnt lgkmcnt(0)
	s_barrier
	s_mov_b64 s[60:61], -1
	s_and_b64 vcc, exec, s[54:55]
	s_cbranch_vccz .LBB0_554
	s_and_b64 vcc, exec, s[58:59]
	s_cbranch_vccz .LBB0_551
	s_andn2_b64 vcc, exec, s[18:19]
	s_cbranch_vccnz .LBB0_550
	s_waitcnt vmcnt(11)
